# prologue next-item prefetch: 32 per-element 64-bit multiply addresses replaced by base plus running stride (address strength reduction), on top of v46
# baseline (speedup 1.0000x reference)
; __device__ __forceinline__ void tr_matrix(const float* W, int ldw, int K, int N, bf16* WT, int mode, const float* kscale, float* scr, int gw, int NGW, int lane) {
;     ...
;         for (int i = 0; i < 32; ++i) { const int kk = 2 * i + (lane >> 5); scr[kk * 33 + (lane & 31)] = kscale ? nx[i] * kscale[k0 + kk] : nx[i]; }
;         if (it + NGW < nitems) { const int kb2 = (it + NGW) / nblk, nb2 = (it + NGW) % nblk;
; #pragma unroll
;             for (int i = 0; i < 32; ++i) { const int kk = 2 * i + (lane >> 5); nx[i] = W[(size_t)(64 * kb2 + kk) * ldw + 32 * nb2 + (lane & 31)]; } }
.LBB0_100:
	v_add_u32_e32 v86, s3, v86
	v_cmp_gt_i32_e64 s[4:5], s48, v86
	v_cmp_le_i32_e32 vcc, s48, v86
	ds_write_b32 v83, v88
	s_and_saveexec_b64 s[24:25], s[4:5]
	s_cbranch_execz .LBB0_35
	v_sub_u32_e32 v5, 0, v86
	v_max_i32_e32 v5, v86, v5
	v_mul_hi_u32 v6, v5, v3
	v_mul_lo_u32 v7, v6, s6
	v_sub_u32_e32 v5, v5, v7
	v_add_u32_e32 v7, 1, v6
	v_cmp_le_u32_e64 s[4:5], s6, v5
	v_ashrrev_i32_e32 v4, 31, v86
	s_nop 0
	v_cndmask_b32_e64 v6, v6, v7, s[4:5]
	v_subrev_u32_e32 v7, s6, v5
	v_cndmask_b32_e64 v5, v5, v7, s[4:5]
	v_add_u32_e32 v7, 1, v6
	v_cmp_le_u32_e64 s[4:5], s6, v5
	s_nop 1
	v_cndmask_b32_e64 v5, v6, v7, s[4:5]
	v_xor_b32_e32 v5, v5, v4
	v_sub_u32_e32 v4, v5, v4
	v_lshlrev_b32_e32 v6, 6, v4
	v_mul_lo_u32 v4, s26, v4
	v_add3_u32 v4, v41, s51, v4
	v_ashrrev_i32_e32 v5, 31, v4
	v_or_b32_e32 v96, v6, v36
	v_lshl_add_u64 v[28:29], v[4:5], 2, v[44:45]
	v_ashrrev_i32_e32 v4, 31, v6
	v_mul_lo_u32 v98, s14, v4
	v_mul_lo_u32 v6, s15, v96
	v_mad_u64_u32 v[4:5], s[4:5], s14, v96, 0
	v_add3_u32 v5, v5, v98, v6
	v_lshl_add_u64 v[88:89], v[4:5], 2, v[28:29]
	s_lshl_b64 s[4:5], s[14:15], 3
	global_load_dword v4, v[88:89], off
	v_lshl_add_u64 v[88:89], s[4:5], 0, v[88:89]
	global_load_dword v5, v[88:89], off
	v_lshl_add_u64 v[88:89], s[4:5], 0, v[88:89]
	global_load_dword v6, v[88:89], off
	v_lshl_add_u64 v[88:89], s[4:5], 0, v[88:89]
	global_load_dword v7, v[88:89], off
	v_lshl_add_u64 v[88:89], s[4:5], 0, v[88:89]
	global_load_dword v8, v[88:89], off
	v_lshl_add_u64 v[88:89], s[4:5], 0, v[88:89]
	global_load_dword v9, v[88:89], off
	v_lshl_add_u64 v[88:89], s[4:5], 0, v[88:89]
	global_load_dword v10, v[88:89], off
	v_lshl_add_u64 v[88:89], s[4:5], 0, v[88:89]
	global_load_dword v11, v[88:89], off
	v_lshl_add_u64 v[88:89], s[4:5], 0, v[88:89]
	global_load_dword v12, v[88:89], off
	v_lshl_add_u64 v[88:89], s[4:5], 0, v[88:89]
	global_load_dword v13, v[88:89], off
	v_lshl_add_u64 v[88:89], s[4:5], 0, v[88:89]
	global_load_dword v14, v[88:89], off
	v_lshl_add_u64 v[88:89], s[4:5], 0, v[88:89]
	global_load_dword v15, v[88:89], off
	v_lshl_add_u64 v[88:89], s[4:5], 0, v[88:89]
	global_load_dword v16, v[88:89], off
	v_lshl_add_u64 v[88:89], s[4:5], 0, v[88:89]
	global_load_dword v17, v[88:89], off
	v_lshl_add_u64 v[88:89], s[4:5], 0, v[88:89]
	global_load_dword v18, v[88:89], off
	v_lshl_add_u64 v[88:89], s[4:5], 0, v[88:89]
	global_load_dword v19, v[88:89], off
	v_lshl_add_u64 v[88:89], s[4:5], 0, v[88:89]
	global_load_dword v20, v[88:89], off
	v_lshl_add_u64 v[88:89], s[4:5], 0, v[88:89]
	global_load_dword v21, v[88:89], off
	v_lshl_add_u64 v[88:89], s[4:5], 0, v[88:89]
	global_load_dword v22, v[88:89], off
	v_lshl_add_u64 v[88:89], s[4:5], 0, v[88:89]
	global_load_dword v23, v[88:89], off
	v_lshl_add_u64 v[88:89], s[4:5], 0, v[88:89]
	global_load_dword v24, v[88:89], off
	v_lshl_add_u64 v[88:89], s[4:5], 0, v[88:89]
	global_load_dword v25, v[88:89], off
	v_lshl_add_u64 v[88:89], s[4:5], 0, v[88:89]
	global_load_dword v26, v[88:89], off
	v_lshl_add_u64 v[88:89], s[4:5], 0, v[88:89]
	global_load_dword v27, v[88:89], off
	v_lshl_add_u64 v[88:89], s[4:5], 0, v[88:89]
	global_load_dword v28, v[88:89], off
	v_lshl_add_u64 v[88:89], s[4:5], 0, v[88:89]
	global_load_dword v29, v[88:89], off
	v_lshl_add_u64 v[88:89], s[4:5], 0, v[88:89]
	global_load_dword v30, v[88:89], off
	v_lshl_add_u64 v[88:89], s[4:5], 0, v[88:89]
	global_load_dword v31, v[88:89], off
	v_lshl_add_u64 v[88:89], s[4:5], 0, v[88:89]
	global_load_dword v32, v[88:89], off
	v_lshl_add_u64 v[88:89], s[4:5], 0, v[88:89]
	global_load_dword v33, v[88:89], off
	v_lshl_add_u64 v[88:89], s[4:5], 0, v[88:89]
	global_load_dword v34, v[88:89], off
	v_lshl_add_u64 v[88:89], s[4:5], 0, v[88:89]
	global_load_dword v35, v[88:89], off
	s_branch .LBB0_35
